# halfround restricted to the last layer (the other layers keep the 6th-round idle half of the grid for the deferred weight conversion)
# speedup vs baseline: 1.0386x; 1.0199x over previous
.LBB0_228:
	s_add_i32 s49, s49, 1
	s_mul_hi_u32 s0, s49, 0xcccccccd
	s_lshr_b32 s8, s0, 2
	s_and_b64 s[0:1], s[24:25], exec
	s_cselect_b32 s0, s49, s8
	s_mul_i32 s1, s0, s53
	s_mul_hi_u32 s4, s0, s33
	s_add_i32 s1, s4, s1
	s_mul_i32 s0, s0, s33
	s_add_u32 s4, s0, s80
	s_addc_u32 s5, s1, s82
	s_mov_b32 s100, 0
	s_cmpk_lg_u32 s34, 0x580
	s_cbranch_scc1 .Lhr_done
	s_cmpk_lg_u32 s33, 0x100
	s_cbranch_scc1 .Lhr_done
	s_cmp_lt_u32 s44, 35
	s_cbranch_scc1 .Lhr_done
	s_cmpk_lt_u32 s4, 0x500
	s_cbranch_scc1 .Lhr_done
	s_mov_b32 s100, 1
	s_cmpk_lt_u32 s4, 0x580
	s_cbranch_scc1 .Lhr_done
	s_mov_b32 s100, 0
	s_cmpk_gt_u32 s4, 0x5ff
	s_cbranch_scc1 .Lhr_done
	s_movk_i32 s100, 0x81
	s_add_i32 s4, s4, 0xffffff80
